# NA: 8 gate loads hoisted with counted vmcnt waits; tile 0/8 bias-table LDS lookups batched into 16 temporaries (one LDS round trip instead of 16)
# speedup vs baseline: 1.0161x; 1.0161x over previous
; __device__ __forceinline__ unsigned cvtpk(float lo, float hi) { f32x2_t v = {lo, hi}; bf16x2_t b = __builtin_convertvector(v, bf16x2_t); return __builtin_bit_cast(unsigned, b); }
; __device__ __forceinline__ float silu(float g) { return g * __builtin_amdgcn_rcpf(1.0f + __builtin_amdgcn_exp2f(g * -1.4426950408889634f)); }
; __device__ __forceinline__ float xh_sum(float v) { auto rr = __builtin_amdgcn_permlane32_swap(__float_as_uint(v), __float_as_uint(v), false, false); return __uint_as_float(rr[0]) + __uint_as_float(rr[1]); }
; __device__ __forceinline__ void na_unit(LAS unsigned char* lds, const bf16_t* __restrict__ proj, bf16_t* __restrict__ y, int unit, const float* __restrict__ rpb) {
;     ...
;     l = xh_sum(l);
;     const float il = __builtin_amdgcn_rcpf(l);
;     const size_t tok = rowbase + r * 64 + c;
;     const bf16_t* gp = proj + tok * 4096 + 1536 + h * 64;
;     bf16_t* yp = y + tok * 1024 + h * 64;
; #pragma unroll
;     for (int dt = 0; dt < 2; ++dt)
; #pragma unroll
;         for (int g = 0; g < 4; ++g) {
;             const int d = dt * 32 + 8 * g + 4 * hh;
;             const u32x2 gv = *(const u32x2*)(gp + d);
;             const float g0 = __uint_as_float(gv.x << 16), g1 = __uint_as_float(gv.x & 0xffff0000u), g2 = __uint_as_float(gv.y << 16), g3 = __uint_as_float(gv.y & 0xffff0000u);
;             u32x2 w; w.x = cvtpk(o[dt][4 * g] * il * silu(g0), o[dt][4 * g + 1] * il * silu(g1));
;             w.y = cvtpk(o[dt][4 * g + 2] * il * silu(g2), o[dt][4 * g + 3] * il * silu(g3));
;             *(u32x2*)(yp + d) = w;
;         }
.LBB0_192:
	v_lshlrev_b64 v[34:35], 11, v[128:129]
	v_lshl_add_u64 v[34:35], s[48:49], 0, v[34:35]
	v_lshlrev_b32_e32 v152, 3, v132
	v_lshl_add_u64 v[36:37], v[34:35], 0, s[40:41]
	v_lshl_add_u64 v[34:35], v[126:127], 0, v[152:153]
	global_load_dwordx2 v[232:233], v[34:35], off offset:3072
	global_load_dwordx2 v[234:235], v[34:35], off offset:3088
	global_load_dwordx2 v[236:237], v[34:35], off offset:3104
	global_load_dwordx2 v[238:239], v[34:35], off offset:3120
	global_load_dwordx2 v[240:241], v[34:35], off offset:3136
	global_load_dwordx2 v[242:243], v[34:35], off offset:3152
	global_load_dwordx2 v[244:245], v[34:35], off offset:3168
	global_load_dwordx2 v[246:247], v[34:35], off offset:3184
	v_mov_b32_e32 v32, v48
	s_nop 1
	v_permlane32_swap_b32_e32 v48, v32
	v_add_f32_e32 v32, v48, v32
	v_rcp_f32_e32 v32, v32
	s_add_i32 s96, s96, s3
	s_add_i32 s74, s74, s62
	s_cmpk_gt_i32 s96, 0x7ff
	s_waitcnt vmcnt(7)
	v_mov_b32_e32 v38, v232
	v_mov_b32_e32 v39, v233
	v_lshlrev_b32_e32 v40, 16, v38
	v_mul_f32_e32 v33, 0xbfb8aa3b, v40
	v_exp_f32_e32 v33, v33
	v_and_b32_e32 v41, 0xffff0000, v38
	v_add_f32_e32 v33, 1.0, v33
	v_rcp_f32_e32 v42, v33
	v_pk_mul_f32 v[16:17], v[16:17], v[32:33] op_sel_hi:[1,0]
	v_mul_f32_e32 v33, 0xbfb8aa3b, v41
	v_exp_f32_e32 v33, v33
	s_nop 0
	v_add_f32_e32 v33, 1.0, v33
	v_rcp_f32_e32 v43, v33
	s_nop 0
	v_pk_mul_f32 v[40:41], v[42:43], v[40:41]
	s_nop 0
	v_pk_mul_f32 v[16:17], v[16:17], v[40:41]
	s_nop 0
	v_cvt_pk_bf16_f32 v38, v16, v17
	v_lshlrev_b32_e32 v16, 16, v39
	v_mul_f32_e32 v33, 0xbfb8aa3b, v16
	v_exp_f32_e32 v33, v33
	v_and_b32_e32 v17, 0xffff0000, v39
	v_add_f32_e32 v33, 1.0, v33
	v_rcp_f32_e32 v40, v33
	v_pk_mul_f32 v[18:19], v[18:19], v[32:33] op_sel_hi:[1,0]
	v_mul_f32_e32 v33, 0xbfb8aa3b, v17
	v_exp_f32_e32 v33, v33
	s_nop 0
	v_add_f32_e32 v33, 1.0, v33
	v_rcp_f32_e32 v41, v33
	v_pk_mul_f32 v[20:21], v[20:21], v[32:33] op_sel_hi:[1,0]
	v_pk_mul_f32 v[22:23], v[22:23], v[32:33] op_sel_hi:[1,0]
	v_pk_mul_f32 v[24:25], v[24:25], v[32:33] op_sel_hi:[1,0]
	v_pk_mul_f32 v[16:17], v[40:41], v[16:17]
	v_pk_mul_f32 v[0:1], v[0:1], v[32:33] op_sel_hi:[1,0]
	v_pk_mul_f32 v[16:17], v[18:19], v[16:17]
	v_cvt_pk_bf16_f32 v39, v16, v17
	v_lshl_add_u64 v[16:17], v[36:37], 0, v[152:153]
	global_store_dwordx2 v[16:17], v[38:39], off
	v_pk_mul_f32 v[2:3], v[2:3], v[32:33] op_sel_hi:[1,0]
	v_pk_mul_f32 v[4:5], v[4:5], v[32:33] op_sel_hi:[1,0]
	v_pk_mul_f32 v[6:7], v[6:7], v[32:33] op_sel_hi:[1,0]
	s_waitcnt vmcnt(7)
	v_mov_b32_e32 v18, v234
	v_mov_b32_e32 v19, v235
	v_lshlrev_b32_e32 v36, 16, v18
	v_and_b32_e32 v37, 0xffff0000, v18
	v_mul_f32_e32 v18, 0xbfb8aa3b, v36
	v_exp_f32_e32 v18, v18
	s_nop 0
	v_add_f32_e32 v18, 1.0, v18
	v_rcp_f32_e32 v38, v18
	v_mul_f32_e32 v18, 0xbfb8aa3b, v37
	v_exp_f32_e32 v18, v18
	s_nop 0
	v_add_f32_e32 v18, 1.0, v18
	v_rcp_f32_e32 v39, v18
	s_nop 0
	v_pk_mul_f32 v[36:37], v[38:39], v[36:37]
	s_nop 0
	v_pk_mul_f32 v[20:21], v[20:21], v[36:37]
	s_nop 0
	v_cvt_pk_bf16_f32 v18, v20, v21
	v_lshlrev_b32_e32 v20, 16, v19
	v_and_b32_e32 v21, 0xffff0000, v19
	v_mul_f32_e32 v19, 0xbfb8aa3b, v20
	v_exp_f32_e32 v19, v19
	s_nop 0
	v_add_f32_e32 v19, 1.0, v19
	v_rcp_f32_e32 v36, v19
	v_mul_f32_e32 v19, 0xbfb8aa3b, v21
	v_exp_f32_e32 v19, v19
	s_nop 0
	v_add_f32_e32 v19, 1.0, v19
	v_rcp_f32_e32 v37, v19
	s_nop 0
	v_pk_mul_f32 v[20:21], v[36:37], v[20:21]
	s_nop 0
	v_pk_mul_f32 v[20:21], v[22:23], v[20:21]
	s_nop 0
	v_cvt_pk_bf16_f32 v19, v20, v21
	global_store_dwordx2 v[16:17], v[18:19], off offset:16
	s_waitcnt vmcnt(7)
	v_mov_b32_e32 v18, v236
	v_mov_b32_e32 v19, v237
	v_lshlrev_b32_e32 v20, 16, v18
	v_and_b32_e32 v21, 0xffff0000, v18
	v_mul_f32_e32 v18, 0xbfb8aa3b, v20
	v_exp_f32_e32 v18, v18
	s_nop 0
	v_add_f32_e32 v18, 1.0, v18
	v_rcp_f32_e32 v22, v18
	v_mul_f32_e32 v18, 0xbfb8aa3b, v21
	v_exp_f32_e32 v18, v18
	s_nop 0
	v_add_f32_e32 v18, 1.0, v18
	v_rcp_f32_e32 v23, v18
	s_nop 0
	v_pk_mul_f32 v[20:21], v[22:23], v[20:21]
	s_nop 0
	v_pk_mul_f32 v[20:21], v[24:25], v[20:21]
	v_pk_mul_f32 v[24:25], v[26:27], v[32:33] op_sel_hi:[1,0]
	v_cvt_pk_bf16_f32 v18, v20, v21
	v_lshlrev_b32_e32 v20, 16, v19
	v_and_b32_e32 v21, 0xffff0000, v19
	v_mul_f32_e32 v19, 0xbfb8aa3b, v20
	v_exp_f32_e32 v19, v19
	s_nop 0
	v_add_f32_e32 v19, 1.0, v19
	v_rcp_f32_e32 v22, v19
	v_mul_f32_e32 v19, 0xbfb8aa3b, v21
	v_exp_f32_e32 v19, v19
	s_nop 0
	v_add_f32_e32 v19, 1.0, v19
	v_rcp_f32_e32 v23, v19
	s_nop 0
	v_pk_mul_f32 v[20:21], v[22:23], v[20:21]
	s_nop 0
	v_pk_mul_f32 v[20:21], v[24:25], v[20:21]
	v_pk_mul_f32 v[24:25], v[28:29], v[32:33] op_sel_hi:[1,0]
	v_cvt_pk_bf16_f32 v19, v20, v21
	global_store_dwordx2 v[16:17], v[18:19], off offset:32
	s_waitcnt vmcnt(7)
; __device__ __forceinline__ unsigned cvtpk(float lo, float hi) { f32x2_t v = {lo, hi}; bf16x2_t b = __builtin_convertvector(v, bf16x2_t); return __builtin_bit_cast(unsigned, b); }
; __device__ __forceinline__ float silu(float g) { return g * __builtin_amdgcn_rcpf(1.0f + __builtin_amdgcn_exp2f(g * -1.4426950408889634f)); }
; __device__ __forceinline__ void na_unit(LAS unsigned char* lds, const bf16_t* __restrict__ proj, bf16_t* __restrict__ y, int unit, const float* __restrict__ rpb) {
;     ...
;     for (int dt = 0; dt < 2; ++dt)
; #pragma unroll
;         for (int g = 0; g < 4; ++g) {
;             const int d = dt * 32 + 8 * g + 4 * hh;
;             const u32x2 gv = *(const u32x2*)(gp + d);
;             const float g0 = __uint_as_float(gv.x << 16), g1 = __uint_as_float(gv.x & 0xffff0000u), g2 = __uint_as_float(gv.y << 16), g3 = __uint_as_float(gv.y & 0xffff0000u);
;             u32x2 w; w.x = cvtpk(o[dt][4 * g] * il * silu(g0), o[dt][4 * g + 1] * il * silu(g1));
;             w.y = cvtpk(o[dt][4 * g + 2] * il * silu(g2), o[dt][4 * g + 3] * il * silu(g3));
;             *(u32x2*)(yp + d) = w;
;         }
	v_mov_b32_e32 v18, v238
	v_mov_b32_e32 v19, v239
	v_lshlrev_b32_e32 v20, 16, v18
	v_and_b32_e32 v21, 0xffff0000, v18
	v_mul_f32_e32 v18, 0xbfb8aa3b, v20
	v_exp_f32_e32 v18, v18
	s_nop 0
	v_add_f32_e32 v18, 1.0, v18
	v_rcp_f32_e32 v22, v18
	v_mul_f32_e32 v18, 0xbfb8aa3b, v21
	v_exp_f32_e32 v18, v18
	s_nop 0
	v_add_f32_e32 v18, 1.0, v18
	v_rcp_f32_e32 v23, v18
	s_nop 0
	v_pk_mul_f32 v[20:21], v[22:23], v[20:21]
	s_nop 0
	v_pk_mul_f32 v[20:21], v[24:25], v[20:21]
	v_pk_mul_f32 v[24:25], v[30:31], v[32:33] op_sel_hi:[1,0]
	v_cvt_pk_bf16_f32 v18, v20, v21
	v_lshlrev_b32_e32 v20, 16, v19
	v_and_b32_e32 v21, 0xffff0000, v19
	v_mul_f32_e32 v19, 0xbfb8aa3b, v20
	v_exp_f32_e32 v19, v19
	s_nop 0
	v_add_f32_e32 v19, 1.0, v19
	v_rcp_f32_e32 v22, v19
	v_mul_f32_e32 v19, 0xbfb8aa3b, v21
	v_exp_f32_e32 v19, v19
	s_nop 0
	v_add_f32_e32 v19, 1.0, v19
	v_rcp_f32_e32 v23, v19
	s_nop 0
	v_pk_mul_f32 v[20:21], v[22:23], v[20:21]
	s_nop 0
	v_pk_mul_f32 v[20:21], v[24:25], v[20:21]
	s_nop 0
	v_cvt_pk_bf16_f32 v19, v20, v21
	global_store_dwordx2 v[16:17], v[18:19], off offset:48
	s_waitcnt vmcnt(7)
	v_mov_b32_e32 v18, v240
	v_mov_b32_e32 v19, v241
	v_lshlrev_b32_e32 v20, 16, v18
	v_and_b32_e32 v21, 0xffff0000, v18
	v_mul_f32_e32 v18, 0xbfb8aa3b, v20
	v_exp_f32_e32 v18, v18
	s_nop 0
	v_add_f32_e32 v18, 1.0, v18
	v_rcp_f32_e32 v22, v18
	v_mul_f32_e32 v18, 0xbfb8aa3b, v21
	v_exp_f32_e32 v18, v18
	s_nop 0
	v_add_f32_e32 v18, 1.0, v18
	v_rcp_f32_e32 v23, v18
	v_lshlrev_b32_e32 v18, 16, v19
	v_and_b32_e32 v19, 0xffff0000, v19
	v_pk_mul_f32 v[20:21], v[22:23], v[20:21]
	s_nop 0
	v_pk_mul_f32 v[0:1], v[0:1], v[20:21]
	s_nop 0
	v_cvt_pk_bf16_f32 v0, v0, v1
	v_mul_f32_e32 v1, 0xbfb8aa3b, v18
	v_exp_f32_e32 v1, v1
	s_nop 0
	v_add_f32_e32 v1, 1.0, v1
	v_rcp_f32_e32 v20, v1
	v_mul_f32_e32 v1, 0xbfb8aa3b, v19
	v_exp_f32_e32 v1, v1
	s_nop 0
	v_add_f32_e32 v1, 1.0, v1
	v_rcp_f32_e32 v21, v1
	s_nop 0
	v_pk_mul_f32 v[18:19], v[20:21], v[18:19]
	s_nop 0
	v_pk_mul_f32 v[2:3], v[2:3], v[18:19]
	s_nop 0
	v_cvt_pk_bf16_f32 v1, v2, v3
	global_store_dwordx2 v[16:17], v[0:1], off offset:64
	s_waitcnt vmcnt(7)
	v_mov_b32_e32 v0, v242
	v_mov_b32_e32 v1, v243
	v_lshlrev_b32_e32 v2, 16, v0
	v_and_b32_e32 v3, 0xffff0000, v0
	v_mul_f32_e32 v0, 0xbfb8aa3b, v2
	v_exp_f32_e32 v0, v0
	s_nop 0
	v_add_f32_e32 v0, 1.0, v0
	v_rcp_f32_e32 v18, v0
	v_mul_f32_e32 v0, 0xbfb8aa3b, v3
	v_exp_f32_e32 v0, v0
	s_nop 0
	v_add_f32_e32 v0, 1.0, v0
	v_rcp_f32_e32 v19, v0
	s_nop 0
	v_pk_mul_f32 v[2:3], v[18:19], v[2:3]
	s_nop 0
	v_pk_mul_f32 v[2:3], v[4:5], v[2:3]
	s_nop 0
	v_cvt_pk_bf16_f32 v0, v2, v3
	v_lshlrev_b32_e32 v2, 16, v1
	v_and_b32_e32 v3, 0xffff0000, v1
	v_mul_f32_e32 v1, 0xbfb8aa3b, v2
	v_exp_f32_e32 v1, v1
	s_nop 0
	v_add_f32_e32 v1, 1.0, v1
	v_rcp_f32_e32 v4, v1
	v_mul_f32_e32 v1, 0xbfb8aa3b, v3
	v_exp_f32_e32 v1, v1
	s_nop 0
	v_add_f32_e32 v1, 1.0, v1
	v_rcp_f32_e32 v5, v1
	s_nop 0
	v_pk_mul_f32 v[2:3], v[4:5], v[2:3]
	s_nop 0
	v_pk_mul_f32 v[2:3], v[6:7], v[2:3]
	v_pk_mul_f32 v[6:7], v[8:9], v[32:33] op_sel_hi:[1,0]
	v_cvt_pk_bf16_f32 v1, v2, v3
	global_store_dwordx2 v[16:17], v[0:1], off offset:80
	s_waitcnt vmcnt(7)
	v_mov_b32_e32 v0, v244
	v_mov_b32_e32 v1, v245
	v_lshlrev_b32_e32 v2, 16, v0
	v_and_b32_e32 v3, 0xffff0000, v0
	v_mul_f32_e32 v0, 0xbfb8aa3b, v2
	v_exp_f32_e32 v0, v0
	s_nop 0
	v_add_f32_e32 v0, 1.0, v0
	v_rcp_f32_e32 v4, v0
	v_mul_f32_e32 v0, 0xbfb8aa3b, v3
	v_exp_f32_e32 v0, v0
	s_nop 0
	v_add_f32_e32 v0, 1.0, v0
	v_rcp_f32_e32 v5, v0
	s_nop 0
	v_pk_mul_f32 v[2:3], v[4:5], v[2:3]
	s_nop 0
	v_pk_mul_f32 v[2:3], v[6:7], v[2:3]
	v_pk_mul_f32 v[6:7], v[10:11], v[32:33] op_sel_hi:[1,0]
	v_cvt_pk_bf16_f32 v0, v2, v3
	v_lshlrev_b32_e32 v2, 16, v1
	v_and_b32_e32 v3, 0xffff0000, v1
	v_mul_f32_e32 v1, 0xbfb8aa3b, v2
	v_exp_f32_e32 v1, v1
	s_nop 0
	v_add_f32_e32 v1, 1.0, v1
	v_rcp_f32_e32 v4, v1
	v_mul_f32_e32 v1, 0xbfb8aa3b, v3
	v_exp_f32_e32 v1, v1
	s_nop 0
	v_add_f32_e32 v1, 1.0, v1
	v_rcp_f32_e32 v5, v1
	s_nop 0
	v_pk_mul_f32 v[2:3], v[4:5], v[2:3]
	s_nop 0
	v_pk_mul_f32 v[2:3], v[6:7], v[2:3]
	v_pk_mul_f32 v[6:7], v[12:13], v[32:33] op_sel_hi:[1,0]
	v_cvt_pk_bf16_f32 v1, v2, v3
	global_store_dwordx2 v[16:17], v[0:1], off offset:96
	s_waitcnt vmcnt(7)
	v_mov_b32_e32 v0, v246
	v_mov_b32_e32 v1, v247
	v_lshlrev_b32_e32 v2, 16, v0
	v_and_b32_e32 v3, 0xffff0000, v0
	v_mul_f32_e32 v0, 0xbfb8aa3b, v2
	v_exp_f32_e32 v0, v0
	s_nop 0
	v_add_f32_e32 v0, 1.0, v0
	v_rcp_f32_e32 v4, v0
	v_mul_f32_e32 v0, 0xbfb8aa3b, v3
	v_exp_f32_e32 v0, v0
	s_nop 0
	v_add_f32_e32 v0, 1.0, v0
	v_rcp_f32_e32 v5, v0
	s_nop 0
	v_pk_mul_f32 v[2:3], v[4:5], v[2:3]
	s_nop 0
	v_pk_mul_f32 v[2:3], v[6:7], v[2:3]
	v_pk_mul_f32 v[6:7], v[14:15], v[32:33] op_sel_hi:[1,0]
	v_cvt_pk_bf16_f32 v0, v2, v3
	v_lshlrev_b32_e32 v2, 16, v1
	v_and_b32_e32 v3, 0xffff0000, v1
	v_mul_f32_e32 v1, 0xbfb8aa3b, v2
	v_exp_f32_e32 v1, v1
	s_nop 0
	v_add_f32_e32 v1, 1.0, v1
	v_rcp_f32_e32 v4, v1
	v_mul_f32_e32 v1, 0xbfb8aa3b, v3
	v_exp_f32_e32 v1, v1
	s_nop 0
	v_add_f32_e32 v1, 1.0, v1
	v_rcp_f32_e32 v5, v1
	s_nop 0
	v_pk_mul_f32 v[2:3], v[4:5], v[2:3]
	s_nop 0
	v_pk_mul_f32 v[2:3], v[6:7], v[2:3]
	s_nop 0
	v_cvt_pk_bf16_f32 v1, v2, v3
	global_store_dwordx2 v[16:17], v[0:1], off offset:112
	s_cbranch_scc1 .LBB0_241

; #define LAS __attribute__((address_space(3)))
; __device__ __forceinline__ int crow(int r, int hi) { return (r & 3) + 8 * (r >> 2) + 4 * hi; }
; __device__ __forceinline__ void na_unit(LAS unsigned char* lds, const bf16_t* __restrict__ proj, bf16_t* __restrict__ y, int unit, const float* __restrict__ rpb) {
;     ...
;     const int rf = r0 + 2 * (wid >> 2), kblk = wid & 3, c0 = 16 * kblk;
;     const int r = rf + (l31 >> 4), c = c0 + (l31 & 15), rs = clampi(r - 4, 0, 56), cs = clampi(c - 8, 0, 48);
;     const int rst = clampi(rf - 4, 0, 56), ntile = clampi(rf - 3, 0, 56) - rst + 8;
;     const bf16_t* qp = proj + (rowbase + r * 64 + c) * 4096 + h * 64 + hh * 8;
;     bf16x8 qf[4];
; #pragma unroll
;     for (int ks = 0; ks < 4; ++ks) qf[ks] = *(const bf16x8*)(qp + ks * 16);
;     unsigned cpk[4];
; #pragma unroll
;     for (int w = 0; w < 4; ++w) { unsigned v = 0u;
; #pragma unroll
;         for (int e4 = 0; e4 < 4; ++e4) { const int kcol = c0 - 8 + crow(4 * w + e4, hh); const bool valid = (kcol >= cs) && (kcol <= cs + 15);
;             v |= (unsigned)(valid ? kcol - c + 15 : 31) << (8 * e4); }
;         cpk[w] = v; }
;     f32x16 o[2];
; #pragma unroll
;     for (int t = 0; t < 2; ++t)
; #pragma unroll
;         for (int rr = 0; rr < 16; ++rr) o[t][rr] = 0.f;
;     float m = M_INIT, l = 0.f;
;     const bf16_t* kbase = proj + (rowbase + rst * 64 + clampi(c0 - 8 + l31, 0, 63)) * 4096 + 512 + h * 64 + hh * 8;
;     ...
;     const unsigned vrd = (unsigned)(l31 * 128) ^ (unsigned)((hh ^ vsw(l31)) << 4);
;     const unsigned xa0 = (unsigned)(2 * clampi(kblk - 1, 0, 3)) << 4, xb0 = (unsigned)(2 * kblk) << 4, xa1 = xb0, xb1 = (unsigned)(2 * clampi(kblk + 1, 0, 3)) << 4;
;     bf16x8 kq[4][4];
; #pragma unroll
;     for (int t = 0; t < 3; ++t)
; #pragma unroll
;         for (int ks = 0; ks < 4; ++ks) kq[t][ks] = *(const bf16x8*)(NA_KPTR(t) + ks * 16);
; #pragma unroll
;     for (int t = 0; t < 9; ++t) {
;         if (t < 8 || ntile == 9) {
;         { const int tl = (t + 3 < ntile) ? t + 3 : ntile - 1;
; #pragma unroll
;           for (int ks = 0; ks < 4; ++ks) kq[(t + 3) & 3][ks] = *(const bf16x8*)(NA_KPTR(tl) + ks * 16); }
;         const int krow = rst + t;
;         const LAS float* trow = tbl + (((krow >= rs) && (krow <= rs + 7)) ? krow - r + 7 : 15) * 32;
;         const unsigned vslot = (unsigned)(uintptr_t)(lds + (krow - rlo) * NA_SLOT) + vrd;
.LBB0_203:
	s_or_b64 exec, exec, s[36:37]
	s_ashr_i32 s5, s0, 7
	s_and_b32 s5, s5, -2
	s_add_i32 s1, s5, s1
	s_waitcnt vmcnt(1)
	v_lshrrev_b32_e32 v0, 4, v44
	v_or_b32_e32 v133, s1, v0
	s_bfe_u32 s5, s0, 0x20006
	v_lshlrev_b32_e32 v0, 6, v133
	s_lshl_b32 s0, s5, 4
	v_and_b32_e32 v3, 15, v45
	v_ashrrev_i32_e32 v1, 31, v0
	s_waitcnt vmcnt(0)
	v_or_b32_e32 v4, s0, v3
	v_lshl_add_u64 v[128:129], s[30:31], 0, v[0:1]
	v_or_b32_e32 v128, v128, v4
	v_lshlrev_b64 v[0:1], 13, v[128:129]
	v_bfe_u32 v132, v45, 5, 1
	v_lshl_add_u64 v[0:1], s[60:61], 0, v[0:1]
	s_lshl_b32 s40, s7, 1
	v_lshl_add_u64 v[126:127], v[0:1], 0, s[40:41]
	v_lshlrev_b32_e32 v152, 4, v132
	v_lshrrev_b32_e32 v2, 5, v45
	v_lshl_add_u64 v[0:1], v[126:127], 0, v[152:153]
	s_waitcnt lgkmcnt(0)
	s_barrier
	v_med3_u32 v6, v4, 8, 56
	global_load_dwordx4 v[50:53], v[0:1], off
	global_load_dwordx4 v[54:57], v[0:1], off offset:32
	global_load_dwordx4 v[58:61], v[0:1], off offset:64
	global_load_dwordx4 v[62:65], v[0:1], off offset:96
	v_lshl_or_b32 v1, v2, 2, -8
	v_add_u32_e32 v0, -8, v6
	v_add_u32_e32 v2, s0, v1
	v_add_u32_e32 v6, 7, v6
	v_cmp_ge_i32_e32 vcc, v2, v0
	v_cmp_le_i32_e64 s[36:37], v2, v6
	s_and_b64 vcc, vcc, s[36:37]
	v_xad_u32 v7, v3, 15, v1
	v_cndmask_b32_e32 v28, 31, v7, vcc
	v_or_b32_e32 v7, 1, v2
	v_cmp_ge_i32_e32 vcc, v7, v0
	v_cmp_lt_i32_e64 s[36:37], v2, v6
	v_sub_u32_e32 v7, v7, v4
	s_and_b64 vcc, vcc, s[36:37]
	v_lshl_add_u32 v7, v7, 8, v214
	v_or_b32_e32 v8, 2, v2
	v_cndmask_b32_e32 v7, v215, v7, vcc
	v_cmp_ge_i32_e32 vcc, v8, v0
	v_cmp_le_i32_e64 s[36:37], v8, v6
	v_sub_u32_e32 v8, v8, v4
	s_and_b64 vcc, vcc, s[36:37]
	v_lshl_add_u32 v8, v8, 16, v216
	v_or_b32_e32 v9, 3, v2
	v_cndmask_b32_e32 v8, v217, v8, vcc
	v_cmp_ge_i32_e32 vcc, v9, v0
	v_cmp_le_i32_e64 s[36:37], v9, v6
	v_sub_u32_e32 v9, v9, v4
	s_and_b64 vcc, vcc, s[36:37]
	v_lshl_add_u32 v9, v9, 24, v218
	v_cndmask_b32_e32 v9, v219, v9, vcc
	v_or_b32_e32 v8, v8, v9
	v_or3_b32 v29, v8, v7, v28
	v_add_u32_e32 v7, 8, v2
	v_cmp_ge_u32_e32 vcc, v7, v0
	v_cmp_le_u32_e64 s[36:37], v7, v6
	v_sub_u32_e32 v1, v1, v3
	s_and_b64 vcc, vcc, s[36:37]
	v_add_u32_e32 v3, 23, v1
	v_cndmask_b32_e32 v135, 31, v3, vcc
	v_add_u32_e32 v3, 9, v2
	v_cmp_ge_u32_e32 vcc, v3, v0
	v_cmp_le_u32_e64 s[36:37], v3, v6
	v_sub_u32_e32 v3, v3, v4
	s_and_b64 vcc, vcc, s[36:37]
	v_lshl_add_u32 v3, v3, 8, v214
	v_add_u32_e32 v7, 10, v2
	v_cndmask_b32_e32 v3, v215, v3, vcc
	v_cmp_ge_u32_e32 vcc, v7, v0
	v_cmp_le_u32_e64 s[36:37], v7, v6
	v_sub_u32_e32 v7, v7, v4
	s_and_b64 vcc, vcc, s[36:37]
	v_lshl_add_u32 v7, v7, 16, v216
	v_add_u32_e32 v8, 11, v2
	v_cndmask_b32_e32 v7, v217, v7, vcc
	v_cmp_ge_u32_e32 vcc, v8, v0
	v_cmp_le_u32_e64 s[36:37], v8, v6
	v_sub_u32_e32 v8, v8, v4
	s_and_b64 vcc, vcc, s[36:37]
	v_lshl_add_u32 v8, v8, 24, v218
	v_cndmask_b32_e32 v8, v219, v8, vcc
	v_or_b32_e32 v7, v7, v8
	v_or3_b32 v31, v7, v3, v135
	v_add_u32_e32 v3, 16, v2
	v_cmp_ge_u32_e32 vcc, v3, v0
	v_cmp_le_u32_e64 s[36:37], v3, v6
	s_and_b64 vcc, vcc, s[36:37]
	v_add_u32_e32 v3, 31, v1
	v_cndmask_b32_e32 v134, 31, v3, vcc
	v_add_u32_e32 v3, 17, v2
	v_cmp_ge_u32_e32 vcc, v3, v0
	v_cmp_le_u32_e64 s[36:37], v3, v6
	v_sub_u32_e32 v3, v3, v4
	s_and_b64 vcc, vcc, s[36:37]
	v_lshl_add_u32 v3, v3, 8, v214
	v_add_u32_e32 v7, 18, v2
	v_cndmask_b32_e32 v3, v215, v3, vcc
	v_cmp_ge_u32_e32 vcc, v7, v0
	v_cmp_le_u32_e64 s[36:37], v7, v6
	v_sub_u32_e32 v7, v7, v4
	s_and_b64 vcc, vcc, s[36:37]
	v_lshl_add_u32 v7, v7, 16, v216
	v_add_u32_e32 v8, 19, v2
	v_cndmask_b32_e32 v7, v217, v7, vcc
	v_cmp_ge_u32_e32 vcc, v8, v0
	v_cmp_le_u32_e64 s[36:37], v8, v6
	v_sub_u32_e32 v8, v8, v4
	s_and_b64 vcc, vcc, s[36:37]
	v_lshl_add_u32 v8, v8, 24, v218
	v_cndmask_b32_e32 v8, v219, v8, vcc
	v_or_b32_e32 v7, v7, v8
	v_or3_b32 v30, v7, v3, v134
	v_add_u32_e32 v3, 24, v2
	v_cmp_ge_u32_e32 vcc, v3, v0
	v_cmp_le_u32_e64 s[36:37], v3, v6
	s_and_b64 vcc, vcc, s[36:37]
	v_add_u32_e32 v1, 39, v1
	v_cndmask_b32_e32 v137, 31, v1, vcc
	v_add_u32_e32 v1, 25, v2
	v_cmp_ge_u32_e32 vcc, v1, v0
	v_cmp_le_u32_e64 s[36:37], v1, v6
	v_sub_u32_e32 v1, v1, v4
	s_and_b64 vcc, vcc, s[36:37]
	v_lshl_add_u32 v1, v1, 8, v214
	v_add_u32_e32 v3, 26, v2
	v_cndmask_b32_e32 v1, v215, v1, vcc
	v_cmp_ge_u32_e32 vcc, v3, v0
	v_cmp_le_u32_e64 s[36:37], v3, v6
	v_sub_u32_e32 v3, v3, v4
	s_max_i32 s77, s1, 4
	s_and_b64 vcc, vcc, s[36:37]
	v_lshl_add_u32 v3, v3, 16, v216
	v_add_u32_e32 v2, 27, v2
	s_min_i32 s76, s77, 60
	v_cndmask_b32_e32 v3, v217, v3, vcc
	v_cmp_ge_u32_e32 vcc, v2, v0
	v_cmp_le_u32_e64 s[36:37], v2, v6
	v_sub_u32_e32 v0, v2, v4
	s_add_i32 s6, s76, -4
	s_and_b64 vcc, vcc, s[36:37]
	v_lshl_add_u32 v0, v0, 24, v218
	v_med3_i32 v136, s1, 3, 59
	v_cndmask_b32_e32 v0, v219, v0, vcc
	s_lshl_b32 s1, s6, 6
	v_or3_b32 v32, v3, v0, v1
	s_add_u32 s1, s30, s1
	v_add3_u32 v0, v44, s0, -8
	s_addc_u32 s7, s31, 0
	v_med3_i32 v0, v0, 0, 63
	v_or_b32_e32 v0, s1, v0
	v_mov_b32_e32 v1, s7
	v_lshlrev_b64 v[0:1], 13, v[0:1]
	v_lshl_add_u64 v[0:1], s[60:61], 0, v[0:1]
	v_lshl_add_u64 v[0:1], v[0:1], 0, s[40:41]
	v_lshl_add_u64 v[130:131], v[0:1], 0, v[152:153]
	s_mov_b32 s0, 0x80000
	v_add_co_u32_e32 v0, vcc, s0, v130
	s_mov_b32 s0, 0x100000
	s_nop 0
	v_addc_co_u32_e32 v1, vcc, 0, v131, vcc
	global_load_dwordx4 v[94:97], v[0:1], off offset:1024
	global_load_dwordx4 v[86:89], v[0:1], off offset:1056
	global_load_dwordx4 v[114:117], v[0:1], off offset:1088
	global_load_dwordx4 v[98:101], v[0:1], off offset:1120
	v_add_co_u32_e32 v0, vcc, s0, v130
	v_readfirstlane_b32 s0, v136
	s_nop 0
	v_addc_co_u32_e32 v1, vcc, 0, v131, vcc
	global_load_dwordx4 v[90:93], v[0:1], off offset:1024
	global_load_dwordx4 v[82:85], v[0:1], off offset:1056
	global_load_dwordx4 v[118:121], v[0:1], off offset:1088
	global_load_dwordx4 v[106:109], v[0:1], off offset:1120
	global_load_dwordx4 v[16:19], v[130:131], off offset:1120
	global_load_dwordx4 v[20:23], v[130:131], off offset:1088
	global_load_dwordx4 v[24:27], v[130:131], off offset:1056
	s_nop 0
	global_load_dwordx4 v[0:3], v[130:131], off offset:1024
	s_sub_i32 s1, s0, s76
	s_add_i32 s0, s1, 8
	s_cmp_lt_i32 s1, -5
	s_cselect_b32 s8, s0, 3
	v_max_i32_e32 v141, 4, v133
	s_ashr_i32 s9, s8, 31
	v_min_i32_e32 v5, 60, v141
	s_lshl_b64 s[8:9], s[8:9], 19
	v_add_u32_e32 v138, -4, v5
	v_add_u32_e32 v139, 3, v5
	v_lshl_add_u64 v[4:5], v[130:131], 0, s[8:9]
	global_load_dwordx4 v[78:81], v[4:5], off offset:1024
	global_load_dwordx4 v[74:77], v[4:5], off offset:1056
	global_load_dwordx4 v[70:73], v[4:5], off offset:1088
	global_load_dwordx4 v[66:69], v[4:5], off offset:1120
	v_cmp_lt_u32_e32 vcc, s6, v138
	v_cmp_gt_u32_e64 s[36:37], s6, v139
	v_sub_u32_e32 v4, s6, v133
	s_or_b64 vcc, vcc, s[36:37]
	v_lshl_add_u32 v4, v4, 5, v220
	v_cndmask_b32_e32 v4, v4, v221, vcc
	s_add_i32 s78, 0, 0x16000
	v_lshl_add_u32 v33, v4, 2, s78
	s_waitcnt vmcnt(4)
; __device__ __forceinline__ float ex2(float x) { return __builtin_amdgcn_exp2f(x); }
; __device__ __forceinline__ f32x16 mfma32(bf16x8 a, bf16x8 b, f32x16 c) { return __builtin_amdgcn_mfma_f32_32x32x16_bf16(a, b, c, 0, 0, 0); }
; __device__ __forceinline__ float xh_max(float v) { auto rr = __builtin_amdgcn_permlane32_swap(__float_as_uint(v), __float_as_uint(v), false, false); return fmaxf(__uint_as_float(rr[0]), __uint_as_float(rr[1])); }
; template <int NT> __device__ __forceinline__ void softmax_step(f32x16& z, float& m, float& l, f32x16 (&o)[NT], u32x4& p0, u32x4& p1) {
;     float e[16], su = 0.f;
; #pragma unroll
;     for (int r = 0; r < 16; ++r) { e[r] = ex2(z[r] - m); su += e[r]; }
;     if (__builtin_amdgcn_ballot_w64(!(su < 1048576.0f)) != 0ull) {
;         float zm = fmaxf(fmaxf(z[0], z[1]), fmaxf(z[2], z[3]));
; #pragma unroll
;         for (int r = 4; r < 16; r += 4) zm = fmaxf(zm, fmaxf(fmaxf(z[r], z[r + 1]), fmaxf(z[r + 2], z[r + 3])));
;         zm = xh_max(zm);
;         const bool need = zm > m + 8.0f;
;         const float mn = need ? zm : m;
;         const float f = ex2(m - mn);
;         l *= f;
; #pragma unroll
;         for (int t = 0; t < NT; ++t)
; #pragma unroll
;             for (int r = 0; r < 16; ++r) o[t][r] *= f;
;         m = mn;
;         su = 0.f;
; #pragma unroll
;         for (int r = 0; r < 16; ++r) { e[r] = ex2(z[r] - m); su += e[r]; }
;     }
; __device__ __forceinline__ void na_unit(LAS unsigned char* lds, const bf16_t* __restrict__ proj, bf16_t* __restrict__ y, int unit, const float* __restrict__ rpb) {
;     ...
;         f32x16 s;
;         { f32x16 z;
; #pragma unroll
;           for (int rr = 0; rr < 16; ++rr) z[rr] = 0.f;
;           s = mfma32(kq[t & 3][0], qf[0], z); }
; #pragma unroll
;         for (int ks = 1; ks < 4; ++ks) s = mfma32(kq[t & 3][ks], qf[ks], s);
; #pragma unroll
;         for (int rr = 0; rr < 16; ++rr) { const unsigned ci = (cpk[rr >> 2] >> (8 * (rr & 3))) & 0xffu; s[rr] = s[rr] * QK_C + trow[ci]; }
;         u32x4 p0, p1;
;         softmax_step<2>(s, m, l, o, p0, p1);
	v_mfma_f32_32x32x16_bf16 v[0:15], v[0:3], v[50:53], 0
	v_and_b32_e32 v152, 0xff, v28
	v_bfe_u32 v147, v29, 8, 8
	v_bfe_u32 v149, v29, 16, 8
	v_lshrrev_b32_e32 v150, 24, v29
	v_bfe_u32 v151, v31, 8, 8
	v_bfe_u32 v155, v31, 16, 8
	v_lshrrev_b32_e32 v164, 24, v31
	v_mfma_f32_32x32x16_bf16 v[0:15], v[24:27], v[54:57], v[0:15]
	v_bfe_u32 v142, v30, 8, 8
	v_bfe_u32 v143, v30, 16, 8
	v_lshrrev_b32_e32 v144, 24, v30
	v_bfe_u32 v145, v32, 8, 8
	v_bfe_u32 v146, v32, 16, 8
	v_lshrrev_b32_e32 v148, 24, v32
	v_mfma_f32_32x32x16_bf16 v[0:15], v[20:23], v[58:61], v[0:15]
	v_mfma_f32_32x32x16_bf16 v[0:15], v[16:19], v[62:65], v[0:15]
	v_lshl_add_u32 v232, v152, 2, v33
	v_lshl_add_u32 v233, v147, 2, v33
	v_lshl_add_u32 v234, v149, 2, v33
	v_lshl_add_u32 v235, v150, 2, v33
	v_lshl_add_u32 v236, v135, 2, v33
	v_lshl_add_u32 v237, v151, 2, v33
	v_lshl_add_u32 v238, v155, 2, v33
	v_lshl_add_u32 v239, v164, 2, v33
	v_lshl_add_u32 v240, v134, 2, v33
	v_lshl_add_u32 v241, v142, 2, v33
	v_lshl_add_u32 v242, v143, 2, v33
	v_lshl_add_u32 v243, v144, 2, v33
	v_lshl_add_u32 v244, v137, 2, v33
	v_lshl_add_u32 v245, v145, 2, v33
	v_lshl_add_u32 v246, v146, 2, v33
	v_lshl_add_u32 v247, v148, 2, v33
	ds_read_b32 v232, v232
	ds_read_b32 v233, v233
	ds_read_b32 v234, v234
	ds_read_b32 v235, v235
	ds_read_b32 v236, v236
	ds_read_b32 v237, v237
	ds_read_b32 v238, v238
	ds_read_b32 v239, v239
	ds_read_b32 v240, v240
	ds_read_b32 v241, v241
	ds_read_b32 v242, v242
	ds_read_b32 v243, v243
	ds_read_b32 v244, v244
	ds_read_b32 v245, v245
	ds_read_b32 v246, v246
	ds_read_b32 v247, v247
	s_waitcnt lgkmcnt(0)
	s_nop 8
	v_fmamk_f32 v16, v0, 0x3e38aa3b, v232
	s_waitcnt lgkmcnt(0)
	v_fmamk_f32 v0, v1, 0x3e38aa3b, v233
	s_waitcnt lgkmcnt(0)
	v_fmamk_f32 v1, v2, 0x3e38aa3b, v234
	s_waitcnt lgkmcnt(0)
	v_fmamk_f32 v2, v3, 0x3e38aa3b, v235
	s_waitcnt lgkmcnt(0)
	v_fmamk_f32 v3, v4, 0x3e38aa3b, v236
	s_waitcnt lgkmcnt(0)
	v_fmamk_f32 v4, v5, 0x3e38aa3b, v237
	v_add_f32_e32 v22, 0x7149f2ca, v4
	v_exp_f32_e32 v22, v22
	s_waitcnt lgkmcnt(0)
	v_fmamk_f32 v5, v6, 0x3e38aa3b, v238
	s_waitcnt lgkmcnt(0)
	v_fmamk_f32 v6, v7, 0x3e38aa3b, v239
	s_waitcnt lgkmcnt(0)
	v_fmamk_f32 v7, v8, 0x3e38aa3b, v240
	v_add_f32_e32 v25, 0x7149f2ca, v7
	v_exp_f32_e32 v48, v25
	s_waitcnt lgkmcnt(0)
	v_fmamk_f32 v8, v9, 0x3e38aa3b, v241
	v_add_f32_e32 v25, 0x7149f2ca, v8
	v_exp_f32_e32 v49, v25
	s_waitcnt lgkmcnt(0)
	v_fmamk_f32 v9, v10, 0x3e38aa3b, v242
	v_add_f32_e32 v25, 0x7149f2ca, v9
	v_exp_f32_e32 v102, v25
	s_waitcnt lgkmcnt(0)
	v_fmamk_f32 v10, v11, 0x3e38aa3b, v243
	v_add_f32_e32 v25, 0x7149f2ca, v10
	v_exp_f32_e32 v103, v25
	s_waitcnt lgkmcnt(0)
	v_fmamk_f32 v11, v12, 0x3e38aa3b, v244
	v_add_f32_e32 v25, 0x7149f2ca, v11
	v_exp_f32_e32 v104, v25
	s_waitcnt lgkmcnt(0)
	v_fmamk_f32 v12, v13, 0x3e38aa3b, v245
	v_add_f32_e32 v25, 0x7149f2ca, v12
	v_exp_f32_e32 v105, v25
	s_waitcnt lgkmcnt(0)
	v_fmamk_f32 v13, v14, 0x3e38aa3b, v246
	v_add_f32_e32 v14, 0x7149f2ca, v16
	v_exp_f32_e32 v14, v14
	v_add_f32_e32 v25, 0x7149f2ca, v13
	v_exp_f32_e32 v110, v25
	s_waitcnt lgkmcnt(0)
	v_fmamk_f32 v18, v15, 0x3e38aa3b, v247
	v_add_f32_e32 v15, 0x7149f2ca, v0
	v_exp_f32_e32 v15, v15
	v_add_f32_e32 v17, 0, v14
	v_add_f32_e32 v25, 0x7149f2ca, v18
	v_exp_f32_e32 v111, v25
	v_add_f32_e32 v19, v15, v17
	v_add_f32_e32 v17, 0x7149f2ca, v1
	v_exp_f32_e32 v17, v17
	s_nop 0
	v_add_f32_e32 v20, v17, v19
	v_add_f32_e32 v19, 0x7149f2ca, v2
	v_exp_f32_e32 v19, v19
	s_nop 0
	v_add_f32_e32 v21, v19, v20
	v_add_f32_e32 v20, 0x7149f2ca, v3
	v_exp_f32_e32 v20, v20
	s_nop 0
	v_add_f32_e32 v21, v20, v21
	v_add_f32_e32 v23, v22, v21
	v_add_f32_e32 v21, 0x7149f2ca, v5
	v_exp_f32_e32 v21, v21
	s_nop 0
	v_add_f32_e32 v24, v21, v23
	v_add_f32_e32 v23, 0x7149f2ca, v6
	v_exp_f32_e32 v23, v23
	s_nop 0
	v_add_f32_e32 v24, v23, v24
	v_add_f32_e32 v24, v48, v24
	v_add_f32_e32 v24, v49, v24
	v_add_f32_e32 v24, v102, v24
	v_add_f32_e32 v24, v103, v24
	v_add_f32_e32 v24, v104, v24
	v_add_f32_e32 v24, v105, v24
	v_add_f32_e32 v24, v110, v24
	v_add_f32_e32 v122, v111, v24
	v_cmp_ngt_f32_e32 vcc, s68, v122
	s_cbranch_vccz .LBB0_209
	v_max_f32_e32 v14, v0, v0
	v_max_f32_e32 v15, v16, v16
	v_max_f32_e32 v14, v15, v14
	v_max_f32_e32 v15, v2, v2
	v_max_f32_e32 v17, v1, v1
	v_max_f32_e32 v15, v17, v15
	v_max_f32_e32 v17, v6, v6
	v_max_f32_e32 v19, v5, v5
	v_max_f32_e32 v17, v19, v17
	v_max3_f32 v17, v3, v4, v17
	v_max3_f32 v14, v14, v15, v17
	v_max_f32_e32 v15, v10, v10
	v_max_f32_e32 v17, v9, v9
	v_max_f32_e32 v15, v17, v15
	v_max_f32_e32 v17, v18, v18
	v_max_f32_e32 v19, v13, v13
	v_max_f32_e32 v17, v19, v17
	v_max3_f32 v15, v7, v8, v15
	v_max3_f32 v17, v11, v12, v17
	v_max3_f32 v14, v14, v15, v17
	v_mov_b32_e32 v15, v14
	s_nop 1
	v_permlane32_swap_b32_e32 v14, v15
	s_mov_b32 s6, 0xf149f2ca
	v_max3_f32 v124, v14, v15, s6
	v_sub_f32_e32 v14, 0xf149f2ca, v124
	v_exp_f32_e32 v14, v14
	v_sub_f32_e32 v0, v0, v124
	v_exp_f32_e32 v15, v0
	v_sub_f32_e32 v0, v1, v124
	v_mul_f32_e32 v32, 0, v14
	v_sub_f32_e32 v14, v16, v124
	v_exp_f32_e32 v14, v14
	v_exp_f32_e32 v17, v0
	v_sub_f32_e32 v0, v2, v124
	v_exp_f32_e32 v19, v0
	v_sub_f32_e32 v1, v3, v124
	v_add_f32_e32 v0, 0, v14
	v_exp_f32_e32 v20, v1
	v_sub_f32_e32 v1, v4, v124
	v_add_f32_e32 v0, v15, v0
	v_exp_f32_e32 v22, v1
	v_sub_f32_e32 v1, v5, v124
	v_add_f32_e32 v0, v17, v0
	v_exp_f32_e32 v21, v1
	v_sub_f32_e32 v1, v6, v124
	v_add_f32_e32 v0, v19, v0
	v_exp_f32_e32 v23, v1
	v_sub_f32_e32 v1, v7, v124
	v_add_f32_e32 v0, v20, v0
	v_exp_f32_e32 v48, v1
	v_sub_f32_e32 v1, v8, v124
	v_add_f32_e32 v0, v22, v0
	v_exp_f32_e32 v49, v1
	v_sub_f32_e32 v1, v9, v124
	v_add_f32_e32 v0, v21, v0
	v_exp_f32_e32 v102, v1
	v_sub_f32_e32 v1, v10, v124
	v_add_f32_e32 v0, v23, v0
	v_exp_f32_e32 v103, v1
	v_sub_f32_e32 v1, v11, v124
	v_add_f32_e32 v0, v48, v0
	v_exp_f32_e32 v104, v1
	v_sub_f32_e32 v1, v12, v124
	v_add_f32_e32 v0, v49, v0
	v_exp_f32_e32 v105, v1
	v_sub_f32_e32 v1, v13, v124
	v_add_f32_e32 v0, v102, v0
	v_exp_f32_e32 v110, v1
	v_sub_f32_e32 v1, v18, v124
	v_add_f32_e32 v0, v103, v0
	v_exp_f32_e32 v111, v1
	v_add_f32_e32 v0, v104, v0
	v_add_f32_e32 v0, v105, v0
	v_add_f32_e32 v0, v110, v0
	v_add_f32_e32 v122, v111, v0
	s_branch .LBB0_210

; #define LAS __attribute__((address_space(3)))
; __device__ __forceinline__ f32x16 mfma32(bf16x8 a, bf16x8 b, f32x16 c) { return __builtin_amdgcn_mfma_f32_32x32x16_bf16(a, b, c, 0, 0, 0); }
; __device__ __forceinline__ void na_unit(LAS unsigned char* lds, const bf16_t* __restrict__ proj, bf16_t* __restrict__ y, int unit, const float* __restrict__ rpb) {
;     ...
;         if (t < 8 || ntile == 9) {
;         { const int tl = (t + 3 < ntile) ? t + 3 : ntile - 1;
; #pragma unroll
;           for (int ks = 0; ks < 4; ++ks) kq[(t + 3) & 3][ks] = *(const bf16x8*)(NA_KPTR(tl) + ks * 16); }
;         const int krow = rst + t;
;         const LAS float* trow = tbl + (((krow >= rs) && (krow <= rs + 7)) ? krow - r + 7 : 15) * 32;
;         const unsigned vslot = (unsigned)(uintptr_t)(lds + (krow - rlo) * NA_SLOT) + vrd;
;         f32x16 s;
;         { f32x16 z;
; #pragma unroll
;           for (int rr = 0; rr < 16; ++rr) z[rr] = 0.f;
;           s = mfma32(kq[t & 3][0], qf[0], z); }
; #pragma unroll
;         for (int ks = 1; ks < 4; ++ks) s = mfma32(kq[t & 3][ks], qf[ks], s);
; #pragma unroll
;         for (int rr = 0; rr < 16; ++rr) { const unsigned ci = (cpk[rr >> 2] >> (8 * (rr & 3))) & 0xffu; s[rr] = s[rr] * QK_C + trow[ci]; }
;         u32x4 p0, p1;
;         softmax_step<2>(s, m, l, o, p0, p1);
; #pragma unroll
;         for (int dt = 0; dt < 2; ++dt) {
;             const unsigned dx = (unsigned)((dt & 1) << 2) << 4, db = dt * 32 * 128;
;             const u32x2 a0 = *(const LAS u32x2*)(uintptr_t)((vslot ^ xa0 ^ dx) + db + 8), b0 = *(const LAS u32x2*)(uintptr_t)((vslot ^ xb0 ^ dx) + db);
;             const u32x2 a1 = *(const LAS u32x2*)(uintptr_t)((vslot ^ xa1 ^ dx) + db + 8), b1 = *(const LAS u32x2*)(uintptr_t)((vslot ^ xb1 ^ dx) + db);
;             const u32x4 v0 = {a0.x, a0.y, b0.x, b0.y}, v1 = {a1.x, a1.y, b1.x, b1.y};
;             o[dt] = mfma32(__builtin_bit_cast(bf16x8, v0), __builtin_bit_cast(bf16x8, p0), o[dt]);
;             o[dt] = mfma32(__builtin_bit_cast(bf16x8, v1), __builtin_bit_cast(bf16x8, p1), o[dt]);
;         }
.LBB0_231:
	s_sub_i32 s0, s0, s75
	s_lshl_b32 s0, s0, 13
	s_add_i32 s0, s0, 0
	v_add_u32_e32 v35, s0, v140
	v_xor_b32_e32 v66, s81, v35
	ds_read2_b64 v[36:39], v66 offset1:1
	v_xor_b32_e32 v67, s80, v35
	ds_read_b64 v[40:41], v67 offset:8
	v_cvt_pk_bf16_f32 v44, v78, v81
	v_cvt_pk_bf16_f32 v45, v76, v79
	s_waitcnt lgkmcnt(1)
	v_mov_b32_e32 v42, v36
	v_mov_b32_e32 v43, v37
	v_cvt_pk_bf16_f32 v46, v82, v84
	v_cvt_pk_bf16_f32 v47, v90, v92
	v_xor_b32_e32 v74, s79, v35
	v_cvt_pk_bf16_f32 v34, v34, v48
	s_waitcnt lgkmcnt(0)
	v_mfma_f32_32x32x16_bf16 v[16:31], v[40:43], v[44:47], v[16:31]
	ds_read_b64 v[40:41], v74
	v_cvt_pk_bf16_f32 v35, v77, v80
	v_cvt_pk_bf16_f32 v36, v83, v85
	v_cvt_pk_bf16_f32 v37, v91, v93
	v_xor_b32_e32 v42, 64, v67
	v_cmp_ne_u32_e32 vcc, s77, v136
	s_and_b64 vcc, exec, vcc
	s_waitcnt lgkmcnt(0)
	v_mfma_f32_32x32x16_bf16 v[16:31], v[38:41], v[34:37], v[16:31]
	v_xor_b32_e32 v38, 64, v66
	v_add_u32_e32 v38, 0x1000, v38
	ds_read2_b64 v[38:41], v38 offset1:1
	ds_read_b64 v[66:67], v42 offset:4104
	v_add_f32_e32 v48, v32, v33
	s_waitcnt lgkmcnt(1)
	v_mov_b32_e32 v68, v38
	v_mov_b32_e32 v69, v39
	v_xor_b32_e32 v38, 64, v74
	ds_read_b64 v[42:43], v38 offset:4096
	s_waitcnt lgkmcnt(1)
	v_mfma_f32_32x32x16_bf16 v[0:15], v[66:69], v[44:47], v[0:15]
	s_waitcnt lgkmcnt(0)
	v_mfma_f32_32x32x16_bf16 v[0:15], v[40:43], v[34:37], v[0:15]
	s_cbranch_vccnz .LBB0_192
	s_add_i32 s76, s76, 4
	v_cmp_lt_u32_e32 vcc, s76, v138
	v_cmp_gt_u32_e64 s[36:37], s76, v139
	v_sub_u32_e32 v32, s76, v133
	s_or_b64 vcc, vcc, s[36:37]
	v_lshl_add_u32 v32, v32, 5, v220
	v_cndmask_b32_e32 v32, v32, v221, vcc
	v_lshl_add_u32 v66, v32, 2, s78
	s_waitcnt vmcnt(3)
	v_mfma_f32_32x32x16_bf16 v[32:47], v[70:73], v[50:53], 0
	v_lshl_add_u32 v232, v152, 2, v66
	v_lshl_add_u32 v233, v147, 2, v66
	v_lshl_add_u32 v234, v149, 2, v66
	v_lshl_add_u32 v235, v150, 2, v66
	v_lshl_add_u32 v236, v135, 2, v66
	v_lshl_add_u32 v237, v151, 2, v66
	v_lshl_add_u32 v238, v155, 2, v66
	v_lshl_add_u32 v239, v164, 2, v66
	v_lshl_add_u32 v240, v134, 2, v66
	v_lshl_add_u32 v241, v142, 2, v66
	v_lshl_add_u32 v242, v143, 2, v66
	v_lshl_add_u32 v243, v144, 2, v66
	v_lshl_add_u32 v244, v137, 2, v66
	v_lshl_add_u32 v245, v145, 2, v66
	v_lshl_add_u32 v246, v146, 2, v66
	v_lshl_add_u32 v247, v148, 2, v66
	ds_read_b32 v232, v232
	ds_read_b32 v233, v233
	ds_read_b32 v234, v234
	ds_read_b32 v235, v235
	ds_read_b32 v236, v236
	ds_read_b32 v237, v237
	ds_read_b32 v238, v238
	ds_read_b32 v239, v239
	ds_read_b32 v240, v240
	ds_read_b32 v241, v241
	ds_read_b32 v242, v242
	ds_read_b32 v243, v243
	ds_read_b32 v244, v244
	ds_read_b32 v245, v245
	ds_read_b32 v246, v246
	ds_read_b32 v247, v247
	s_waitcnt vmcnt(2)
	v_mfma_f32_32x32x16_bf16 v[32:47], v[86:89], v[54:57], v[32:47]
	s_waitcnt vmcnt(1)
	v_mfma_f32_32x32x16_bf16 v[32:47], v[94:97], v[58:61], v[32:47]
	s_waitcnt vmcnt(0)
	v_mfma_f32_32x32x16_bf16 v[32:47], v[98:101], v[62:65], v[32:47]
	s_waitcnt lgkmcnt(0)
	s_nop 10
	v_fmamk_f32 v50, v32, 0x3e38aa3b, v232
	s_waitcnt lgkmcnt(0)
	v_fmamk_f32 v32, v33, 0x3e38aa3b, v233
	s_waitcnt lgkmcnt(0)
	v_fmamk_f32 v33, v34, 0x3e38aa3b, v234
	s_waitcnt lgkmcnt(0)
	v_fmamk_f32 v34, v35, 0x3e38aa3b, v235
	s_waitcnt lgkmcnt(0)
	v_fmamk_f32 v35, v36, 0x3e38aa3b, v236
	s_waitcnt lgkmcnt(0)
	v_fmamk_f32 v36, v37, 0x3e38aa3b, v237
	s_waitcnt lgkmcnt(0)
	v_fmamk_f32 v37, v38, 0x3e38aa3b, v238
	v_sub_f32_e32 v38, v50, v49
	s_waitcnt lgkmcnt(8)
	v_fmamk_f32 v51, v39, 0x3e38aa3b, v239
	v_exp_f32_e32 v38, v38
	v_sub_f32_e32 v39, v32, v49
	v_exp_f32_e32 v39, v39
	s_waitcnt lgkmcnt(7)
	v_fmamk_f32 v52, v40, 0x3e38aa3b, v240
	v_add_f32_e32 v40, 0, v38
	s_waitcnt lgkmcnt(6)
	v_fmamk_f32 v53, v41, 0x3e38aa3b, v241
	v_add_f32_e32 v41, v39, v40
	v_sub_f32_e32 v40, v33, v49
	v_exp_f32_e32 v40, v40
	s_waitcnt lgkmcnt(5)
	v_fmamk_f32 v54, v42, 0x3e38aa3b, v242
	s_waitcnt lgkmcnt(4)
	v_fmamk_f32 v55, v43, 0x3e38aa3b, v243
	s_waitcnt lgkmcnt(3)
	v_fmamk_f32 v56, v44, 0x3e38aa3b, v244
	v_add_f32_e32 v42, v40, v41
	v_sub_f32_e32 v41, v34, v49
	v_exp_f32_e32 v41, v41
	s_waitcnt lgkmcnt(2)
	v_fmamk_f32 v57, v45, 0x3e38aa3b, v245
	s_waitcnt lgkmcnt(1)
	v_fmamk_f32 v58, v46, 0x3e38aa3b, v246
	v_sub_f32_e32 v46, v51, v49
	v_add_f32_e32 v43, v41, v42
	v_sub_f32_e32 v42, v35, v49
	v_exp_f32_e32 v42, v42
	v_exp_f32_e32 v46, v46
	s_waitcnt lgkmcnt(0)
	v_fmamk_f32 v61, v47, 0x3e38aa3b, v247
	v_sub_f32_e32 v63, v56, v49
	v_add_f32_e32 v44, v42, v43
	v_sub_f32_e32 v43, v36, v49
	v_exp_f32_e32 v43, v43
	v_exp_f32_e32 v63, v63
	v_sub_f32_e32 v64, v57, v49
	v_exp_f32_e32 v64, v64
	v_add_f32_e32 v45, v43, v44
	v_sub_f32_e32 v44, v37, v49
	v_exp_f32_e32 v44, v44
	v_sub_f32_e32 v65, v58, v49
	v_exp_f32_e32 v65, v65
	v_sub_f32_e32 v66, v61, v49
	v_add_f32_e32 v45, v44, v45
	v_add_f32_e32 v47, v46, v45
	v_sub_f32_e32 v45, v52, v49
	v_exp_f32_e32 v45, v45
	v_exp_f32_e32 v66, v66
	v_add_f32_e32 v59, v45, v47
	v_sub_f32_e32 v47, v53, v49
	v_exp_f32_e32 v47, v47
	s_nop 0
	v_add_f32_e32 v60, v47, v59
	v_sub_f32_e32 v59, v54, v49
	v_exp_f32_e32 v59, v59
	s_nop 0
	v_add_f32_e32 v62, v59, v60
	v_sub_f32_e32 v60, v55, v49
	v_exp_f32_e32 v60, v60
	s_nop 0
	v_add_f32_e32 v62, v60, v62
	v_add_f32_e32 v62, v63, v62
	v_add_f32_e32 v62, v64, v62
	v_add_f32_e32 v62, v65, v62
	v_add_f32_e32 v62, v66, v62
	v_cmp_ngt_f32_e32 vcc, s68, v62
	s_cbranch_vccz .LBB0_191
; __device__ __forceinline__ float ex2(float x) { return __builtin_amdgcn_exp2f(x); }
; __device__ __forceinline__ float xh_max(float v) { auto rr = __builtin_amdgcn_permlane32_swap(__float_as_uint(v), __float_as_uint(v), false, false); return fmaxf(__uint_as_float(rr[0]), __uint_as_float(rr[1])); }
; template <int NT> __device__ __forceinline__ void softmax_step(f32x16& z, float& m, float& l, f32x16 (&o)[NT], u32x4& p0, u32x4& p1) {
;     ...
;     if (__builtin_amdgcn_ballot_w64(!(su < 1048576.0f)) != 0ull) {
;         float zm = fmaxf(fmaxf(z[0], z[1]), fmaxf(z[2], z[3]));
; #pragma unroll
;         for (int r = 4; r < 16; r += 4) zm = fmaxf(zm, fmaxf(fmaxf(z[r], z[r + 1]), fmaxf(z[r + 2], z[r + 3])));
;         zm = xh_max(zm);
;         const bool need = zm > m + 8.0f;
;         const float mn = need ? zm : m;
;         const float f = ex2(m - mn);
;         l *= f;
; #pragma unroll
;         for (int t = 0; t < NT; ++t)
; #pragma unroll
;             for (int r = 0; r < 16; ++r) o[t][r] *= f;
;         m = mn;
;         su = 0.f;
; #pragma unroll
;         for (int r = 0; r < 16; ++r) { e[r] = ex2(z[r] - m); su += e[r]; }
;     }
	v_max_f32_e32 v38, v32, v32
	v_max_f32_e32 v39, v50, v50
	v_max_f32_e32 v38, v39, v38
	v_max_f32_e32 v39, v34, v34
	v_max_f32_e32 v40, v33, v33
	v_max_f32_e32 v39, v40, v39
	v_max_f32_e32 v40, v51, v51
	v_max_f32_e32 v41, v37, v37
	v_max_f32_e32 v40, v41, v40
	v_max3_f32 v40, v35, v36, v40
	v_max3_f32 v38, v38, v39, v40
	v_max_f32_e32 v39, v55, v55
	v_max_f32_e32 v40, v54, v54
	v_max_f32_e32 v39, v40, v39
	v_max_f32_e32 v40, v61, v61
	v_max_f32_e32 v41, v58, v58
	v_max_f32_e32 v40, v41, v40
	v_max3_f32 v39, v52, v53, v39
	v_max3_f32 v40, v56, v57, v40
	v_max3_f32 v38, v38, v39, v40
	v_mov_b32_e32 v39, v38
	s_nop 1
	v_permlane32_swap_b32_e32 v38, v39
	v_max_f32_e32 v39, v39, v39
	v_max_f32_e32 v38, v38, v38
	v_max_f32_e32 v38, v38, v39
	v_add_f32_e32 v39, 0x41000000, v49
	v_cmp_gt_f32_e32 vcc, v38, v39
	s_nop 1
	v_cndmask_b32_e32 v62, v49, v38, vcc
	v_sub_f32_e32 v38, v49, v62
	v_exp_f32_e32 v38, v38
	v_sub_f32_e32 v32, v32, v62
	v_mul_f32_e32 v48, v48, v38
	v_pk_mul_f32 v[14:15], v[14:15], v[38:39] op_sel_hi:[1,0]
	v_pk_mul_f32 v[12:13], v[12:13], v[38:39] op_sel_hi:[1,0]
	v_pk_mul_f32 v[10:11], v[10:11], v[38:39] op_sel_hi:[1,0]
	v_pk_mul_f32 v[8:9], v[8:9], v[38:39] op_sel_hi:[1,0]
	v_pk_mul_f32 v[6:7], v[6:7], v[38:39] op_sel_hi:[1,0]
	v_pk_mul_f32 v[4:5], v[4:5], v[38:39] op_sel_hi:[1,0]
	v_pk_mul_f32 v[2:3], v[2:3], v[38:39] op_sel_hi:[1,0]
	v_pk_mul_f32 v[0:1], v[0:1], v[38:39] op_sel_hi:[1,0]
	v_pk_mul_f32 v[30:31], v[30:31], v[38:39] op_sel_hi:[1,0]
	v_pk_mul_f32 v[28:29], v[28:29], v[38:39] op_sel_hi:[1,0]
	v_pk_mul_f32 v[26:27], v[26:27], v[38:39] op_sel_hi:[1,0]
	v_pk_mul_f32 v[24:25], v[24:25], v[38:39] op_sel_hi:[1,0]
	v_pk_mul_f32 v[22:23], v[22:23], v[38:39] op_sel_hi:[1,0]
	v_pk_mul_f32 v[20:21], v[20:21], v[38:39] op_sel_hi:[1,0]
	v_pk_mul_f32 v[18:19], v[18:19], v[38:39] op_sel_hi:[1,0]
	v_pk_mul_f32 v[16:17], v[16:17], v[38:39] op_sel_hi:[1,0]
	v_sub_f32_e32 v38, v50, v62
	v_exp_f32_e32 v38, v38
	v_exp_f32_e32 v39, v32
	v_sub_f32_e32 v32, v33, v62
	v_exp_f32_e32 v40, v32
	v_sub_f32_e32 v32, v34, v62
	v_exp_f32_e32 v41, v32
	v_sub_f32_e32 v33, v35, v62
	v_add_f32_e32 v32, 0, v38
	v_exp_f32_e32 v42, v33
	v_sub_f32_e32 v33, v36, v62
	v_add_f32_e32 v32, v39, v32
	v_exp_f32_e32 v43, v33
	v_sub_f32_e32 v33, v37, v62
	v_add_f32_e32 v32, v40, v32
	v_exp_f32_e32 v44, v33
	v_sub_f32_e32 v33, v51, v62
	v_add_f32_e32 v32, v41, v32
	v_exp_f32_e32 v46, v33
	v_sub_f32_e32 v33, v52, v62
	v_add_f32_e32 v32, v42, v32
	v_exp_f32_e32 v45, v33
	v_sub_f32_e32 v33, v53, v62
	v_add_f32_e32 v32, v43, v32
	v_exp_f32_e32 v47, v33
	v_sub_f32_e32 v33, v54, v62
	v_add_f32_e32 v32, v44, v32
	v_exp_f32_e32 v59, v33
	v_sub_f32_e32 v33, v55, v62
	v_add_f32_e32 v32, v46, v32
	v_exp_f32_e32 v60, v33
	v_sub_f32_e32 v33, v56, v62
	v_add_f32_e32 v32, v45, v32
	v_exp_f32_e32 v63, v33
	v_sub_f32_e32 v33, v57, v62
	v_add_f32_e32 v32, v47, v32
	v_exp_f32_e32 v64, v33
	v_sub_f32_e32 v33, v58, v62
	v_add_f32_e32 v32, v59, v32
	v_exp_f32_e32 v65, v33
	v_sub_f32_e32 v33, v61, v62
	v_add_f32_e32 v32, v60, v32
	v_exp_f32_e32 v66, v33
	v_add_f32_e32 v32, v63, v32
	v_add_f32_e32 v32, v64, v32
	v_add_f32_e32 v32, v65, v32
	v_add_f32_e32 v62, v66, v32
	s_branch .LBB0_191
